# HGRN scan: A'/Kd prefetch as 8-byte loads (2 rows per instruction), Kd^T image via permlane32 swap
# speedup vs baseline: 1.0355x; 1.0202x over previous
.LBB0_499:
	s_lshl_b32 s14, s4, 1
	s_or_b32 s14, s14, s11
	s_ashr_i32 s15, s14, 31
	s_lshl_b64 s[14:15], s[14:15], 18
	s_add_u32 s11, s72, s14
	s_addc_u32 s14, s73, s15
	s_lshl_b32 s13, s13, 2
	s_add_u32 s11, s11, s13
	s_addc_u32 s13, s14, 0
	s_lshl_b32 s14, s8, 6
	s_add_u32 s14, s11, s14
	s_addc_u32 s15, s13, 0
	v_lshlrev_b32_e32 v0, 2, v58
	v_lshl_add_u64 v[30:31], s[14:15], 0, v[0:1]
	s_and_b64 s[14:15], exec, s[2:3]
	s_mov_b32 s29, 0
	s_cselect_b32 s28, 0, 0x3f000
	v_lshl_add_u64 v[10:11], v[30:31], 0, s[28:29]
	global_load_dwordx4 v[10:13], v[10:11], off
	s_lshr_b32 s13, s10, 7
	s_lshl_b32 s14, s12, 1
	s_lshl_b32 s38, s13, 4
	s_lshl_b64 s[48:49], s[4:5], 24
	s_cmp_le_u32 s14, s13
	s_cselect_b64 s[30:31], -1, 0
	s_lshl_b32 s39, s12, 5
	s_lshl_b32 s28, s12, 6
	s_or_b32 s40, s14, 1
	v_xor_b32_e32 v0, s8, v63
	s_cmp_lt_u32 s14, s13
	v_lshl_add_u32 v70, v0, 4, v90
	v_xor_b32_e32 v0, v16, v63
	v_lshl_or_b32 v16, s12, 4, v50
	s_cselect_b64 s[34:35], -1, 0
	s_lshl_b32 s12, s40, 4
	s_lshl_b32 s47, s40, 5
	s_and_b64 s[50:51], exec, s[2:3]
	s_cselect_b32 s41, s76, s36
	s_cselect_b32 s40, s77, s33
	s_add_u32 s41, s41, s48
	v_mov_b32_e32 v15, v1
	s_waitcnt vmcnt(22)
	v_or_b32_e32 v18, s39, v50
	s_addc_u32 s40, s40, s49
	v_lshl_add_u32 v71, v0, 4, v92
	v_lshl_add_u64 v[32:33], s[6:7], 0, v[14:15]
	v_or_b32_e32 v0, s38, v50
	s_movk_i32 s6, 0x110
	v_mul_u32_u24_e32 v17, 0x110, v16
	v_mad_u32_u24 v114, v16, s37, 0
	v_lshl_or_b32 v16, s8, 4, v50
	v_mul_u32_u24_e32 v19, 0x110, v18
	v_or_b32_e32 v18, s39, v58
	s_add_u32 s20, s41, s20
	v_mul_lo_u32 v15, v0, s6
	v_mul_lo_u32 v16, v16, s37
	v_cmp_gt_u32_e64 s[4:5], v18, v0
	v_cmp_lt_u32_e64 s[6:7], v18, v0
	v_or_b32_e32 v20, 2, v18
	v_or_b32_e32 v18, 3, v18
	s_addc_u32 s40, s40, 0
	v_add_u32_e32 v115, 0, v16
	v_lshl_add_u32 v16, s8, 5, v94
	s_mulk_i32 s8, 0x880
	s_mulk_i32 s9, 0x110
	v_cmp_gt_u32_e64 s[10:11], v18, v0
	v_or_b32_e32 v18, s12, v50
	s_add_u32 s20, s20, s21
	v_add_u32_e32 v116, s8, v89
	v_add_u32_e32 v117, s9, v89
	v_cmp_gt_u32_e64 s[8:9], v20, v0
	v_mul_u32_u24_e32 v20, 0x110, v18
	v_or_b32_e32 v18, s12, v58
	s_addc_u32 s21, s40, 0
	v_cmp_gt_u32_e64 s[12:13], v18, v0
	v_cmp_lt_u32_e64 s[14:15], v18, v0
	v_or_b32_e32 v21, 2, v18
	v_or_b32_e32 v18, 3, v18
	s_add_u32 s20, s20, s39
	v_mul_lo_u32 v14, v0, s37
	v_cmp_gt_u32_e64 s[16:17], v21, v0
	v_cmp_gt_u32_e64 s[18:19], v18, v0
	s_addc_u32 s21, s21, 0
	v_lshlrev_b32_e32 v0, 1, v50
	v_mov_b32_e32 v18, 0
	s_mov_b32 s46, 1
	v_add_u32_e32 v113, v91, v14
	v_lshl_add_u64 v[34:35], s[20:21], 0, v[0:1]
	v_subrev_u32_e32 v0, s39, v106
	s_sub_i32 s48, 0, s25
	v_or_b32_e32 v118, s38, v58
	v_subrev_u32_e32 v119, s38, v104
	v_or_b32_e32 v120, s39, v74
	s_mov_b32 s49, 62
	v_add_u32_e32 v121, v99, v19
	v_add_u32_e32 v122, v99, v20
	v_add_u32_e32 v123, v100, v17
	v_add_u32_e32 v124, v93, v14
	v_add_u32_e32 v125, v16, v96
	v_add_u32_e32 v126, v99, v15
	s_mov_b32 s50, s29
	v_mov_b32_e32 v19, v18
	v_mov_b32_e32 v20, v18
	v_mov_b32_e32 v21, v18
	v_mov_b32_e32 v14, v18
	v_mov_b32_e32 v15, v18
	v_mov_b32_e32 v16, v18
	v_mov_b32_e32 v17, v18
	s_and_b64 s[94:95], s[2:3], exec
	s_cselect_b32 s93, 0, -1
	v_readfirstlane_b32 s54, v26
	v_readfirstlane_b32 s55, v27
	v_readfirstlane_b32 s56, v28
	v_readfirstlane_b32 s57, v29
	v_readfirstlane_b32 s58, v32
	v_readfirstlane_b32 s59, v33
	v_readfirstlane_b32 s60, v34
	v_readfirstlane_b32 s61, v35
	s_lshl_b32 s94, s24, 1
	s_add_i32 s95, s25, 64
	s_sub_i32 s96, 0xfb8, s25
	s_cmp_eq_u32 s93, 0
	s_cselect_b32 s95, s95, s96
	s_mul_i32 s96, s95, s94
	s_add_u32 s54, s54, s96
	s_addc_u32 s55, s55, 0
	s_mul_i32 s96, s95, 0x4800
	s_add_u32 s56, s56, s96
	s_addc_u32 s57, s57, 0
	s_cmp_eq_u32 s93, 0
	s_cselect_b32 s95, 64, 0xf80
	s_mul_i32 s96, s95, 0x4800
	s_add_u32 s58, s58, s96
	s_addc_u32 s59, s59, 0
	s_and_b32 s96, s93, 0xfc0000
	s_add_u32 s60, s60, s96
	s_addc_u32 s61, s61, 0
	s_lshl_b32 s62, s94, 6
	s_xor_b32 s62, s62, s93
	s_sub_i32 s62, s62, s93
	s_xor_b32 s63, s93, 0x120000
	s_sub_i32 s63, s63, s93
	s_xor_b32 s92, s93, 0x40000
	s_sub_i32 s92, s92, s93
	v_lshlrev_b32_e32 v140, 2, v220
	s_mul_i32 s95, s94, 7
	s_and_b32 s95, s95, s93
	v_add_u32_e32 v140, s95, v140
	s_xor_b32 s95, s94, s93
	s_sub_i32 s95, s95, s93
	v_add_u32_e32 v141, s95, v140
	v_add_u32_e32 v142, s95, v141
	v_add_u32_e32 v143, s95, v142
	v_add_u32_e32 v144, s95, v143
	v_add_u32_e32 v145, s95, v144
	v_add_u32_e32 v146, s95, v145
	v_add_u32_e32 v147, s95, v146
	v_lshlrev_b32_e32 v148, 2, v220
	s_and_b32 s95, s93, 0x1f800
	v_add_u32_e32 v148, s95, v148
	s_xor_b32 s95, s93, 0x4800
	s_sub_i32 s95, s95, s93
	v_add_u32_e32 v149, s95, v148
	v_add_u32_e32 v150, s95, v149
	v_add_u32_e32 v151, s95, v150
	v_add_u32_e32 v152, s95, v151
	v_add_u32_e32 v153, s95, v152
	v_add_u32_e32 v154, s95, v153
	v_add_u32_e32 v155, s95, v154
	s_and_b32 s96, s93, 64
	v_xor_b32_e32 v156, s93, v120
	v_add_u32_e32 v156, s96, v156
	v_mul_u32_u24_e32 v156, 0x4800, v156
	v_lshl_add_u32 v156, v50, 2, v156
	v_add_u32_e32 v157, s95, v156
	v_add_u32_e32 v158, s95, v157
	v_add_u32_e32 v159, s95, v158
	v_add_u32_e32 v160, s95, v159
	v_add_u32_e32 v161, s95, v160
	v_add_u32_e32 v162, s95, v161
	v_add_u32_e32 v163, s95, v162
	v_xor_b32_e32 v164, s93, v118
	v_add_u32_e32 v164, s96, v164
	v_lshlrev_b32_e32 v164, 12, v164
	v_lshl_add_u32 v164, v50, 1, v164
	s_xor_b32 s95, s93, 0x1000
	s_sub_i32 s95, s95, s93
	v_add_u32_e32 v165, s95, v164
	v_add_u32_e32 v166, s95, v165
	v_add_u32_e32 v167, s95, v166
	v_add_u32_e32 v222, v114, v81
	v_add_u32_e32 v223, v114, v82
	v_add_u32_e32 v224, v115, v81
	v_add_u32_e32 v225, v115, v82
	v_add_u32_e32 v226, v95, v81
	v_add_u32_e32 v227, v95, v82
	v_add_u32_e32 v228, s28, v113
	v_add_u32_e32 v229, s47, v113
	v_and_b32_e32 v0, 31, v220
	v_lshrrev_b32_e32 v230, 5, v220
	v_lshl_or_b32 v231, v0, 1, v230
	v_mul_u32_u24_e32 v230, 0x110, v230
	v_lshl_add_u32 v230, v0, 3, v230
	s_mul_i32 s95, s25, 0x110
	v_add_u32_e32 v230, s95, v230
	s_lshr_b32 s95, s25, 3
	v_and_b32_e32 v0, 7, v231
	v_xor_b32_e32 v0, s95, v0
	v_mul_u32_u24_e32 v231, 0x120, v231
	v_lshl_add_u32 v231, v0, 4, v231
	v_lshrrev_b32_e32 v0, 5, v220
	s_and_b32 s95, s93, 7
	v_xor_b32_e32 v0, s95, v0
	v_and_b32_e32 v141, 31, v220
	v_lshlrev_b32_e32 v141, 3, v141
	v_mad_u32_u24 v140, v0, s94, v141
	v_mul_u32_u24_e32 v148, 0x4800, v0
	v_add_u32_e32 v148, v148, v141
	s_lshl_b32 s95, s94, 1
	s_xor_b32 s95, s95, s93
	s_sub_i32 s95, s95, s93
	v_add_u32_e32 v141, s95, v140
	v_add_u32_e32 v142, s95, v141
	v_add_u32_e32 v143, s95, v142
	s_xor_b32 s95, s93, 0x9000
	s_sub_i32 s95, s95, s93
	v_add_u32_e32 v149, s95, v148
	v_add_u32_e32 v150, s95, v149
	v_add_u32_e32 v151, s95, v150
	s_waitcnt vmcnt(0)
	s_sub_u32 s96, s54, s62
	s_subb_u32 s97, s55, s93
	s_sub_u32 s98, s56, s63
	s_subb_u32 s99, s57, s93
	global_load_dwordx2 v[40:41], v140, s[96:97]
	global_load_dwordx2 v[48:49], v148, s[98:99]
	global_load_dwordx2 v[42:43], v141, s[96:97]
	global_load_dwordx2 v[64:65], v149, s[98:99]
	global_load_dwordx2 v[44:45], v142, s[96:97]
	global_load_dwordx2 v[66:67], v150, s[98:99]
	global_load_dwordx2 v[46:47], v143, s[96:97]
	global_load_dwordx2 v[68:69], v151, s[98:99]
	s_waitcnt vmcnt(0)
	s_branch .LBB0_501
.LBB0_501:
	s_waitcnt vmcnt(4)
	ds_write_b64 v230, v[40:41]
	ds_write_b64 v230, v[42:43] offset:544
	ds_write_b64 v230, v[44:45] offset:1088
	ds_write_b64 v230, v[46:47] offset:1632
	ds_write_b64 v230, v[48:49] offset:17408
	ds_write_b64 v230, v[64:65] offset:17952
	ds_write_b64 v230, v[66:67] offset:18496
	ds_write_b64 v230, v[68:69] offset:19040
	v_permlane32_swap_b32 v48, v49
	v_permlane32_swap_b32 v64, v65
	v_permlane32_swap_b32 v66, v67
	v_permlane32_swap_b32 v68, v69
	v_lshlrev_b32_e32 v22, 16, v49
	v_lshlrev_b32_e32 v23, 16, v65
	v_lshlrev_b32_e32 v24, 16, v67
	v_lshlrev_b32_e32 v25, 16, v69
	v_and_or_b32 v22, v48, s43, v22
	v_and_or_b32 v23, v64, s43, v23
	v_and_or_b32 v24, v66, s43, v24
	v_and_or_b32 v25, v68, s43, v25
	v_lshrrev_b32_e32 v36, 16, v48
	v_lshrrev_b32_e32 v37, 16, v64
	v_lshrrev_b32_e32 v38, 16, v66
	v_lshrrev_b32_e32 v39, 16, v68
	ds_write_b128 v231, v[22:25] offset:34816
	v_and_or_b32 v36, v49, s44, v36
	v_and_or_b32 v37, v65, s44, v37
	v_and_or_b32 v38, v67, s44, v38
	v_and_or_b32 v39, v69, s44, v39
	s_andn2_b64 vcc, exec, s[26:27]
	ds_write_b128 v231, v[36:39] offset:34960
	s_cbranch_vccnz .LBB0_503
	v_lshlrev_b32_e32 v22, 16, v3
	v_lshlrev_b32_e32 v23, 16, v5
	v_lshlrev_b32_e32 v24, 16, v7
	v_lshlrev_b32_e32 v25, 16, v9
	v_and_or_b32 v22, v2, s43, v22
	v_and_or_b32 v23, v4, s43, v23
	v_and_or_b32 v24, v6, s43, v24
	v_and_or_b32 v25, v8, s43, v25
	v_lshrrev_b32_e32 v36, 16, v2
	v_lshrrev_b32_e32 v37, 16, v4
	v_lshrrev_b32_e32 v38, 16, v6
	v_lshrrev_b32_e32 v39, 16, v8
	v_and_or_b32 v36, v3, s44, v36
	v_and_or_b32 v37, v5, s44, v37
	v_and_or_b32 v38, v7, s44, v38
	v_and_or_b32 v39, v9, s44, v39
	ds_write_b128 v71, v[22:25] offset:53248
	ds_write_b128 v71, v[36:39] offset:53392
.LBB0_503:
	s_waitcnt lgkmcnt(0)
	s_barrier
	s_andn2_b64 vcc, exec, s[30:31]
	s_cbranch_vccnz .Lhg_v0
	s_andn2_b64 vcc, exec, s[34:35]
	s_cbranch_vccnz .Lhg_v1
	ds_read_b128 v[168:171], v126
	ds_read_b128 v[184:187], v121 offset:17408
	ds_read_b128 v[200:203], v122 offset:17408
	ds_read_b128 v[128:131], v123
	ds_read_b128 v[172:175], v126 offset:64
	ds_read_b128 v[188:191], v121 offset:17472
	ds_read_b128 v[204:207], v122 offset:17472
	ds_read_b128 v[132:135], v123 offset:64
	ds_read_b128 v[176:179], v126 offset:128
	ds_read_b128 v[192:195], v121 offset:17536
	ds_read_b128 v[208:211], v122 offset:17536
	ds_read_b128 v[136:139], v123 offset:128
	ds_read_b128 v[180:183], v126 offset:192
	ds_read_b128 v[196:199], v121 offset:17600
	ds_read_b128 v[212:215], v122 offset:17600
	ds_read_b128 v[216:219], v123 offset:192
	s_cmpk_eq_i32 s50, 0xf040
	s_cbranch_scc1 .Lhg_last_b
	s_and_b64 s[94:95], exec, s[2:3]
	s_cselect_b32 s94, s46, s49
	s_ashr_i32 s95, s94, 31
	s_lshl_b64 s[94:95], s[94:95], 12
	v_lshl_add_u64 v[22:23], v[30:31], 0, s[94:95]
	global_load_dwordx4 v[22:25], v[22:23], off
	global_load_dwordx2 v[40:41], v140, s[54:55]
	global_load_dwordx2 v[48:49], v148, s[56:57]
	global_load_dwordx2 v[42:43], v141, s[54:55]
	global_load_dwordx2 v[64:65], v149, s[56:57]
	global_load_dwordx2 v[44:45], v142, s[54:55]
	global_load_dwordx2 v[66:67], v150, s[56:57]
	global_load_dwordx2 v[46:47], v143, s[54:55]
	global_load_dwordx2 v[68:69], v151, s[56:57]
	s_add_u32 s54, s54, s62
	s_addc_u32 s55, s55, s93
	s_add_u32 s56, s56, s63
	s_addc_u32 s57, s57, s93
	s_andn2_b64 vcc, exec, s[26:27]
	s_cbranch_vccnz .Lhg_ld_done_b
	global_load_dword v2, v156, s[58:59] offset:2048 nt
	global_load_dword v3, v157, s[58:59] offset:2048 nt
	global_load_dword v4, v158, s[58:59] offset:2048 nt
	global_load_dword v5, v159, s[58:59] offset:2048 nt
	global_load_dword v6, v160, s[58:59] offset:2048 nt
	global_load_dword v7, v161, s[58:59] offset:2048 nt
	global_load_dword v8, v162, s[58:59] offset:2048 nt
	global_load_dword v9, v163, s[58:59] offset:2048 nt
	s_add_u32 s58, s58, s63
	s_addc_u32 s59, s59, s93
	s_branch .Lhg_ld_done_b

.Lhg_v1:
	ds_read_b128 v[168:171], v126
	ds_read_b128 v[184:187], v121 offset:17408
	ds_read_b128 v[128:131], v123
	ds_read_b128 v[172:175], v126 offset:64
	ds_read_b128 v[188:191], v121 offset:17472
	ds_read_b128 v[132:135], v123 offset:64
	ds_read_b128 v[176:179], v126 offset:128
	ds_read_b128 v[192:195], v121 offset:17536
	ds_read_b128 v[136:139], v123 offset:128
	ds_read_b128 v[180:183], v126 offset:192
	ds_read_b128 v[196:199], v121 offset:17600
	ds_read_b128 v[216:219], v123 offset:192
	s_cmpk_eq_i32 s50, 0xf040
	s_cbranch_scc1 .Lhg_last_a
	s_and_b64 s[94:95], exec, s[2:3]
	s_cselect_b32 s94, s46, s49
	s_ashr_i32 s95, s94, 31
	s_lshl_b64 s[94:95], s[94:95], 12
	v_lshl_add_u64 v[22:23], v[30:31], 0, s[94:95]
	global_load_dwordx4 v[22:25], v[22:23], off
	global_load_dwordx2 v[40:41], v140, s[54:55]
	global_load_dwordx2 v[48:49], v148, s[56:57]
	global_load_dwordx2 v[42:43], v141, s[54:55]
	global_load_dwordx2 v[64:65], v149, s[56:57]
	global_load_dwordx2 v[44:45], v142, s[54:55]
	global_load_dwordx2 v[66:67], v150, s[56:57]
	global_load_dwordx2 v[46:47], v143, s[54:55]
	global_load_dwordx2 v[68:69], v151, s[56:57]
	s_add_u32 s54, s54, s62
	s_addc_u32 s55, s55, s93
	s_add_u32 s56, s56, s63
	s_addc_u32 s57, s57, s93
	s_andn2_b64 vcc, exec, s[26:27]
	s_cbranch_vccnz .Lhg_ld_done_a
	global_load_dword v2, v156, s[58:59] offset:2048 nt
	global_load_dword v3, v157, s[58:59] offset:2048 nt
	global_load_dword v4, v158, s[58:59] offset:2048 nt
	global_load_dword v5, v159, s[58:59] offset:2048 nt
	global_load_dword v6, v160, s[58:59] offset:2048 nt
	global_load_dword v7, v161, s[58:59] offset:2048 nt
	global_load_dword v8, v162, s[58:59] offset:2048 nt
	global_load_dword v9, v163, s[58:59] offset:2048 nt
	s_add_u32 s58, s58, s63
	s_addc_u32 s59, s59, s93
	s_branch .Lhg_ld_done_a

.Lhg_v0:
	ds_read_b128 v[168:171], v126
	ds_read_b128 v[128:131], v123
	ds_read_b128 v[172:175], v126 offset:64
	ds_read_b128 v[132:135], v123 offset:64
	ds_read_b128 v[176:179], v126 offset:128
	ds_read_b128 v[136:139], v123 offset:128
	ds_read_b128 v[180:183], v126 offset:192
	ds_read_b128 v[216:219], v123 offset:192
	s_cmpk_eq_i32 s50, 0xf040
	s_cbranch_scc1 .Lhg_last_n
	s_and_b64 s[94:95], exec, s[2:3]
	s_cselect_b32 s94, s46, s49
	s_ashr_i32 s95, s94, 31
	s_lshl_b64 s[94:95], s[94:95], 12
	v_lshl_add_u64 v[22:23], v[30:31], 0, s[94:95]
	global_load_dwordx4 v[22:25], v[22:23], off
	global_load_dwordx2 v[40:41], v140, s[54:55]
	global_load_dwordx2 v[48:49], v148, s[56:57]
	global_load_dwordx2 v[42:43], v141, s[54:55]
	global_load_dwordx2 v[64:65], v149, s[56:57]
	global_load_dwordx2 v[44:45], v142, s[54:55]
	global_load_dwordx2 v[66:67], v150, s[56:57]
	global_load_dwordx2 v[46:47], v143, s[54:55]
	global_load_dwordx2 v[68:69], v151, s[56:57]
	s_add_u32 s54, s54, s62
	s_addc_u32 s55, s55, s93
	s_add_u32 s56, s56, s63
	s_addc_u32 s57, s57, s93
	s_andn2_b64 vcc, exec, s[26:27]
	s_cbranch_vccnz .Lhg_ld_done_n
	global_load_dword v2, v156, s[58:59] offset:2048 nt
	global_load_dword v3, v157, s[58:59] offset:2048 nt
	global_load_dword v4, v158, s[58:59] offset:2048 nt
	global_load_dword v5, v159, s[58:59] offset:2048 nt
	global_load_dword v6, v160, s[58:59] offset:2048 nt
	global_load_dword v7, v161, s[58:59] offset:2048 nt
	global_load_dword v8, v162, s[58:59] offset:2048 nt
	global_load_dword v9, v163, s[58:59] offset:2048 nt
	s_add_u32 s58, s58, s63
	s_addc_u32 s59, s59, s93
	s_branch .Lhg_ld_done_n

.Lhg_p3:
	s_waitcnt lgkmcnt(0)
	s_barrier
	ds_read_b128 v[168:171], v124 offset:57856
	ds_read_b128 v[172:175], v222 offset:53248
	ds_read_b128 v[176:179], v224 offset:34816
	ds_read_b128 v[180:183], v226 offset:53248
	ds_read_b128 v[184:187], v226 offset:55552
	ds_read_b128 v[188:191], v124 offset:57920
	ds_read_b128 v[192:195], v223 offset:53248
	ds_read_b128 v[196:199], v225 offset:34816
	ds_read_b128 v[200:203], v227 offset:53248
	ds_read_b128 v[204:207], v227 offset:55552
	s_waitcnt lgkmcnt(8)
	v_mfma_f32_16x16x32_bf16 v[32:35], v[168:171], v[172:175], v[32:35]
	s_waitcnt lgkmcnt(6)
	v_mfma_f32_16x16x32_bf16 v[18:21], v[176:179], v[180:183], v[18:21]
	s_waitcnt lgkmcnt(5)
	v_mfma_f32_16x16x32_bf16 v[10:13], v[176:179], v[184:187], v[10:13]
	s_waitcnt lgkmcnt(3)
	v_mfma_f32_16x16x32_bf16 v[32:35], v[188:191], v[192:195], v[32:35]
	s_waitcnt lgkmcnt(1)
	v_mfma_f32_16x16x32_bf16 v[18:21], v[196:199], v[200:203], v[18:21]
	s_waitcnt lgkmcnt(0)
	v_mfma_f32_16x16x32_bf16 v[14:17], v[196:199], v[204:207], v[10:13]
	s_nop 5
	v_cvt_pk_bf16_f32 v128, v32, s0
	v_cvt_pk_bf16_f32 v129, v33, s0
	v_cvt_pk_bf16_f32 v130, v34, s0
	v_cvt_pk_bf16_f32 v131, v35, s0
	global_store_short v164, v128, s[60:61]
	global_store_short v165, v129, s[60:61]
	global_store_short v166, v130, s[60:61]
	global_store_short v167, v131, s[60:61]
	s_add_u32 s60, s60, s92
	s_addc_u32 s61, s61, s93
	s_andn2_b64 vcc, exec, s[26:27]
	s_cbranch_vccnz .Lhg_dw_hi
	s_waitcnt vmcnt(20)
	s_branch .Lhg_dw_done
.Lhg_dw_hi:
	s_waitcnt vmcnt(12)
